# EpiProj: straight-line rotary epilogue for q_A panels of prompt rows (rope rows from LDS, ds_bpermute partner exchange)
# speedup vs baseline: 1.0331x; 1.0034x over previous
; #define LAS __attribute__((address_space(3)))
;     DI void operator()(f32x4 (&acc)[2][2][4][2], const Unit& u, int wr, int wc, int fr, int fq, LAS unsigned char* lds) const {
;     ...
;         float rsv[8];
;         { const LAS float* tab = (const LAS float*)(lds + RS_OFF) + u.rk * 256 + wr * 64 + fr;
; #pragma unroll
;           for (int i = 0; i < 8; ++i) rsv[i] = tab[(i >> 2) * 128 + (i & 3) * 16]; }
;     ...
;                     const int gcol = u.pn * 256 + bj * 128;
;                     f32x4 v0 = acc[ai][bj][m][0] * rs, v1 = acc[ai][bj][m][1] * rs;
;                     if (gcol < 768 && gcol != 640) {
;                         if (rope_wave) {
;                             const float* rp = ROPE + (size_t)posidx * 16;
;                             const f32x4 cs0 = *(const f32x4*)rp, cs1 = *(const f32x4*)(rp + 4), sn0 = *(const f32x4*)(rp + 8), sn1 = *(const f32x4*)(rp + 12);
;                             f32x4 p0, p1;
; #pragma unroll
;                             for (int j = 0; j < 4; ++j) { p0[j] = __shfl_xor(v0[j], 16); p1[j] = __shfl_xor(v1[j], 16); }
;                             if (fq == 0) { v0 = v0 * cs0 - p0 * sn0; v1 = v1 * cs1 - p1 * sn1; }
;                             else if (fq == 1) { v0 = v0 * cs0 + p0 * sn0; v1 = v1 * cs1 + p1 * sn1; }
;                         }
;                     }
;                     bf16_t* dst; int ld, c0; float* of = nullptr; long orow = -1;
;                     if (gcol < 512) { dst = QA; ld = 512; c0 = gcol; v0 = v0 * QSCALE; v1 = v1 * QSCALE; }
;                     else if (gcol < 640) { dst = KA; ld = 128; c0 = gcol - 512; of = out + (prm ? O_KWP : O_KWS); orow = offA; }
;                     else if (gcol < 768) { dst = VA; ld = 128; c0 = gcol - 640; of = out + (prm ? O_VWP : O_VWS); orow = offA; }
;                     else if (gcol < 1280) { dst = QB; ld = 512; c0 = gcol - 768; v0 = v0 * QSCALE; v1 = v1 * QSCALE; }
;                     else if (gcol < 1792) { dst = KB; ld = 512; c0 = gcol - 1280; of = out + (prm ? O_KBP : O_KBS); orow = offB; }
;                     else if (gcol < 2304) { dst = VB; ld = 512; c0 = gcol - 1792; of = out + (prm ? O_VBP : O_VBS); orow = offB; }
;                     else { dst = GATES; ld = 2048; c0 = gcol - 2304;
.Lrope_pre_skip:
	v_lshl_add_u32 v96, s4, 10, v175
	ds_read2_b32 v[220:221], v96 offset1:16
	ds_read2_b32 v[204:205], v96 offset0:32 offset1:48
	ds_read2_b32 v[198:199], v96 offset0:128 offset1:144
	ds_read2_b32 v[194:195], v96 offset0:160 offset1:176
	v_lshl_add_u32 v192, s96, 8, v171
	s_cmp_gt_i32 s97, 8
	s_cbranch_scc1 .Lepf_gates
	s_cmp_lt_i32 s97, 2
	s_cbranch_scc1 .Lepf_qa
	s_cmp_lt_i32 s97, 3
	s_cbranch_scc1 .Lepf_none
	s_cmp_lt_i32 s97, 5
	s_cbranch_scc1 .Lepf_qb
	s_cmpk_gt_i32 s96, 0x7f
	s_cbranch_scc1 .Lepf_none
	s_and_b32 s0, s96, 31
	s_cmp_gt_i32 s0, 29
	s_cbranch_scc1 .Lepf_none
	s_cmp_lt_i32 s97, 7
	s_cbranch_scc1 .Lepf_kb
	v_readlane_b32 s24, v250, 42
	v_readlane_b32 s25, v250, 43
	s_add_i32 s22, s97, -7
	s_lshl_b32 s22, s22, 9
	s_branch .Lepf_plain

; #define LAS __attribute__((address_space(3)))
;     DI void operator()(f32x4 (&acc)[2][2][4][2], const Unit& u, int wr, int wc, int fr, int fq, LAS unsigned char* lds) const {
;     ...
;                     f32x4 v0 = acc[ai][bj][m][0] * rs, v1 = acc[ai][bj][m][1] * rs;
;                     if (gcol < 768 && gcol != 640) {
;                         if (rope_wave) {
;                             const float* rp = ROPE + (size_t)posidx * 16;
;                             const f32x4 cs0 = *(const f32x4*)rp, cs1 = *(const f32x4*)(rp + 4), sn0 = *(const f32x4*)(rp + 8), sn1 = *(const f32x4*)(rp + 12);
;                             f32x4 p0, p1;
; #pragma unroll
;                             for (int j = 0; j < 4; ++j) { p0[j] = __shfl_xor(v0[j], 16); p1[j] = __shfl_xor(v1[j], 16); }
;                             if (fq == 0) { v0 = v0 * cs0 - p0 * sn0; v1 = v1 * cs1 - p1 * sn1; }
;                             else if (fq == 1) { v0 = v0 * cs0 + p0 * sn0; v1 = v1 * cs1 + p1 * sn1; }
;                         }
;                     }
;                     bf16_t* dst; int ld, c0; float* of = nullptr; long orow = -1;
;                     if (gcol < 512) { dst = QA; ld = 512; c0 = gcol; v0 = v0 * QSCALE; v1 = v1 * QSCALE; }
;                     else if (gcol < 640) { dst = KA; ld = 128; c0 = gcol - 512; of = out + (prm ? O_KWP : O_KWS); orow = offA; }
;                     else if (gcol < 768) { dst = VA; ld = 128; c0 = gcol - 640; of = out + (prm ? O_VWP : O_VWS); orow = offA; }
;                     else if (gcol < 1280) { dst = QB; ld = 512; c0 = gcol - 768; v0 = v0 * QSCALE; v1 = v1 * QSCALE; }
;                     else if (gcol < 1792) { dst = KB; ld = 512; c0 = gcol - 1280; of = out + (prm ? O_KBP : O_KBS); orow = offB; }
;                     else if (gcol < 2304) { dst = VB; ld = 512; c0 = gcol - 1792; of = out + (prm ? O_VBP : O_VBS); orow = offB; }
;                     else { dst = GATES; ld = 2048; c0 = gcol - 2304;
;                         const f32x4 g0 = *(const LAS f32x4*)(lds + BG_OFF + (c0 + cw) * 4), g1 = *(const LAS f32x4*)(lds + BG_OFF + (c0 + cw + 4) * 4);
; #pragma unroll
;                         for (int j = 0; j < 4; ++j) { v0[j] = sigmoidf_(v0[j] + g0[j]); v1[j] = sigmoidf_(v1[j] + g1[j]); } }
;                     u32x4 w; w.x = pk2(v0[0], v0[1]); w.y = pk2(v0[2], v0[3]); w.z = pk2(v1[0], v1[1]); w.w = pk2(v1[2], v1[3]);
.Lepf_qb_body:
	s_waitcnt lgkmcnt(0)
	v_lshlrev_b32_e32 v154, 10, v192
	v_lshl_add_u32 v154, v166, 1, v154
	v_add_u32_e32 v154, s22, v154
	v_mul_f32_e32 v146, v126, v220
	v_mul_f32_e32 v147, v127, v220
	v_mul_f32_e32 v148, v128, v220
	v_mul_f32_e32 v149, v129, v220
	v_mul_f32_e32 v150, v122, v220
	v_mul_f32_e32 v151, v123, v220
	v_mul_f32_e32 v152, v124, v220
	v_mul_f32_e32 v153, v125, v220
	v_mul_f32_e32 v146, s66, v146
	v_mul_f32_e32 v147, s66, v147
	v_mul_f32_e32 v148, s66, v148
	v_mul_f32_e32 v149, s66, v149
	v_mul_f32_e32 v150, s66, v150
	v_mul_f32_e32 v151, s66, v151
	v_mul_f32_e32 v152, s66, v152
	v_mul_f32_e32 v153, s66, v153
	v_add_u32_e32 v156, 0x0, v154
	v_cvt_pk_bf16_f32 v206, v146, v147
	v_cvt_pk_bf16_f32 v207, v148, v149
	v_cvt_pk_bf16_f32 v208, v150, v151
	v_cvt_pk_bf16_f32 v209, v152, v153
	global_store_dwordx4 v156, v[206:209], s[24:25]
	v_mul_f32_e32 v146, v92, v220
	v_mul_f32_e32 v147, v93, v220
	v_mul_f32_e32 v148, v94, v220
	v_mul_f32_e32 v149, v95, v220
	v_mul_f32_e32 v150, v88, v220
	v_mul_f32_e32 v151, v89, v220
	v_mul_f32_e32 v152, v90, v220
	v_mul_f32_e32 v153, v91, v220
	v_mul_f32_e32 v146, s66, v146
	v_mul_f32_e32 v147, s66, v147
	v_mul_f32_e32 v148, s66, v148
	v_mul_f32_e32 v149, s66, v149
	v_mul_f32_e32 v150, s66, v150
	v_mul_f32_e32 v151, s66, v151
	v_mul_f32_e32 v152, s66, v152
	v_mul_f32_e32 v153, s66, v153
	v_add_u32_e32 v156, 0x100, v154
	v_cvt_pk_bf16_f32 v210, v146, v147
	v_cvt_pk_bf16_f32 v211, v148, v149
	v_cvt_pk_bf16_f32 v212, v150, v151
	v_cvt_pk_bf16_f32 v213, v152, v153
	global_store_dwordx4 v156, v[210:213], s[24:25]
	v_mul_f32_e32 v146, v118, v221
	v_mul_f32_e32 v147, v119, v221
	v_mul_f32_e32 v148, v120, v221
	v_mul_f32_e32 v149, v121, v221
	v_mul_f32_e32 v150, v114, v221
	v_mul_f32_e32 v151, v115, v221
	v_mul_f32_e32 v152, v116, v221
	v_mul_f32_e32 v153, v117, v221
	v_mul_f32_e32 v146, s66, v146
	v_mul_f32_e32 v147, s66, v147
	v_mul_f32_e32 v148, s66, v148
	v_mul_f32_e32 v149, s66, v149
	v_mul_f32_e32 v150, s66, v150
	v_mul_f32_e32 v151, s66, v151
	v_mul_f32_e32 v152, s66, v152
	v_mul_f32_e32 v153, s66, v153
	v_add_u32_e32 v156, 0x4000, v154
	v_cvt_pk_bf16_f32 v206, v146, v147
	v_cvt_pk_bf16_f32 v207, v148, v149
	v_cvt_pk_bf16_f32 v208, v150, v151
	v_cvt_pk_bf16_f32 v209, v152, v153
	global_store_dwordx4 v156, v[206:209], s[24:25]
	v_mul_f32_e32 v146, v84, v221
	v_mul_f32_e32 v147, v85, v221
	v_mul_f32_e32 v148, v86, v221
	v_mul_f32_e32 v149, v87, v221
	v_mul_f32_e32 v150, v80, v221
	v_mul_f32_e32 v151, v81, v221
	v_mul_f32_e32 v152, v82, v221
	v_mul_f32_e32 v153, v83, v221
	v_mul_f32_e32 v146, s66, v146
	v_mul_f32_e32 v147, s66, v147
	v_mul_f32_e32 v148, s66, v148
	v_mul_f32_e32 v149, s66, v149
	v_mul_f32_e32 v150, s66, v150
	v_mul_f32_e32 v151, s66, v151
	v_mul_f32_e32 v152, s66, v152
	v_mul_f32_e32 v153, s66, v153
	v_add_u32_e32 v156, 0x4100, v154
	v_cvt_pk_bf16_f32 v210, v146, v147
	v_cvt_pk_bf16_f32 v211, v148, v149
	v_cvt_pk_bf16_f32 v212, v150, v151
	v_cvt_pk_bf16_f32 v213, v152, v153
	global_store_dwordx4 v156, v[210:213], s[24:25]
	v_mul_f32_e32 v146, v110, v204
	v_mul_f32_e32 v147, v111, v204
	v_mul_f32_e32 v148, v112, v204
	v_mul_f32_e32 v149, v113, v204
	v_mul_f32_e32 v150, v106, v204
	v_mul_f32_e32 v151, v107, v204
	v_mul_f32_e32 v152, v108, v204
	v_mul_f32_e32 v153, v109, v204
	v_mul_f32_e32 v146, s66, v146
	v_mul_f32_e32 v147, s66, v147
	v_mul_f32_e32 v148, s66, v148
	v_mul_f32_e32 v149, s66, v149
	v_mul_f32_e32 v150, s66, v150
	v_mul_f32_e32 v151, s66, v151
	v_mul_f32_e32 v152, s66, v152
	v_mul_f32_e32 v153, s66, v153
	v_add_u32_e32 v156, 0x8000, v154
	v_cvt_pk_bf16_f32 v206, v146, v147
	v_cvt_pk_bf16_f32 v207, v148, v149
	v_cvt_pk_bf16_f32 v208, v150, v151
	v_cvt_pk_bf16_f32 v209, v152, v153
	global_store_dwordx4 v156, v[206:209], s[24:25]
	v_mul_f32_e32 v146, v76, v204
	v_mul_f32_e32 v147, v77, v204
	v_mul_f32_e32 v148, v78, v204
	v_mul_f32_e32 v149, v79, v204
	v_mul_f32_e32 v150, v72, v204
	v_mul_f32_e32 v151, v73, v204
	v_mul_f32_e32 v152, v74, v204
	v_mul_f32_e32 v153, v75, v204
	v_mul_f32_e32 v146, s66, v146
	v_mul_f32_e32 v147, s66, v147
	v_mul_f32_e32 v148, s66, v148
	v_mul_f32_e32 v149, s66, v149
	v_mul_f32_e32 v150, s66, v150
	v_mul_f32_e32 v151, s66, v151
	v_mul_f32_e32 v152, s66, v152
	v_mul_f32_e32 v153, s66, v153
	v_add_u32_e32 v156, 0x8100, v154
	v_cvt_pk_bf16_f32 v210, v146, v147
	v_cvt_pk_bf16_f32 v211, v148, v149
	v_cvt_pk_bf16_f32 v212, v150, v151
	v_cvt_pk_bf16_f32 v213, v152, v153
	global_store_dwordx4 v156, v[210:213], s[24:25]
	v_mul_f32_e32 v146, v102, v205
	v_mul_f32_e32 v147, v103, v205
	v_mul_f32_e32 v148, v104, v205
	v_mul_f32_e32 v149, v105, v205
	v_mul_f32_e32 v150, v98, v205
	v_mul_f32_e32 v151, v99, v205
	v_mul_f32_e32 v152, v100, v205
	v_mul_f32_e32 v153, v101, v205
	v_mul_f32_e32 v146, s66, v146
	v_mul_f32_e32 v147, s66, v147
	v_mul_f32_e32 v148, s66, v148
	v_mul_f32_e32 v149, s66, v149
	v_mul_f32_e32 v150, s66, v150
	v_mul_f32_e32 v151, s66, v151
	v_mul_f32_e32 v152, s66, v152
	v_mul_f32_e32 v153, s66, v153
	v_add_u32_e32 v156, 0xc000, v154
	v_cvt_pk_bf16_f32 v206, v146, v147
	v_cvt_pk_bf16_f32 v207, v148, v149
	v_cvt_pk_bf16_f32 v208, v150, v151
	v_cvt_pk_bf16_f32 v209, v152, v153
	global_store_dwordx4 v156, v[206:209], s[24:25]
	v_mul_f32_e32 v146, v68, v205
	v_mul_f32_e32 v147, v69, v205
	v_mul_f32_e32 v148, v70, v205
	v_mul_f32_e32 v149, v71, v205
	v_mul_f32_e32 v150, v64, v205
	v_mul_f32_e32 v151, v65, v205
	v_mul_f32_e32 v152, v66, v205
	v_mul_f32_e32 v153, v67, v205
	v_mul_f32_e32 v146, s66, v146
	v_mul_f32_e32 v147, s66, v147
	v_mul_f32_e32 v148, s66, v148
	v_mul_f32_e32 v149, s66, v149
	v_mul_f32_e32 v150, s66, v150
; #define LAS __attribute__((address_space(3)))
;     DI void operator()(f32x4 (&acc)[2][2][4][2], const Unit& u, int wr, int wc, int fr, int fq, LAS unsigned char* lds) const {
;     ...
;                     f32x4 v0 = acc[ai][bj][m][0] * rs, v1 = acc[ai][bj][m][1] * rs;
;                     if (gcol < 768 && gcol != 640) {
;                         if (rope_wave) {
;                             const float* rp = ROPE + (size_t)posidx * 16;
;                             const f32x4 cs0 = *(const f32x4*)rp, cs1 = *(const f32x4*)(rp + 4), sn0 = *(const f32x4*)(rp + 8), sn1 = *(const f32x4*)(rp + 12);
;                             f32x4 p0, p1;
; #pragma unroll
;                             for (int j = 0; j < 4; ++j) { p0[j] = __shfl_xor(v0[j], 16); p1[j] = __shfl_xor(v1[j], 16); }
;                             if (fq == 0) { v0 = v0 * cs0 - p0 * sn0; v1 = v1 * cs1 - p1 * sn1; }
;                             else if (fq == 1) { v0 = v0 * cs0 + p0 * sn0; v1 = v1 * cs1 + p1 * sn1; }
;                         }
;                     }
;                     bf16_t* dst; int ld, c0; float* of = nullptr; long orow = -1;
;                     if (gcol < 512) { dst = QA; ld = 512; c0 = gcol; v0 = v0 * QSCALE; v1 = v1 * QSCALE; }
;                     else if (gcol < 640) { dst = KA; ld = 128; c0 = gcol - 512; of = out + (prm ? O_KWP : O_KWS); orow = offA; }
;                     else if (gcol < 768) { dst = VA; ld = 128; c0 = gcol - 640; of = out + (prm ? O_VWP : O_VWS); orow = offA; }
;                     else if (gcol < 1280) { dst = QB; ld = 512; c0 = gcol - 768; v0 = v0 * QSCALE; v1 = v1 * QSCALE; }
;                     else if (gcol < 1792) { dst = KB; ld = 512; c0 = gcol - 1280; of = out + (prm ? O_KBP : O_KBS); orow = offB; }
;                     else if (gcol < 2304) { dst = VB; ld = 512; c0 = gcol - 1792; of = out + (prm ? O_VBP : O_VBS); orow = offB; }
;                     else { dst = GATES; ld = 2048; c0 = gcol - 2304;
;                         const f32x4 g0 = *(const LAS f32x4*)(lds + BG_OFF + (c0 + cw) * 4), g1 = *(const LAS f32x4*)(lds + BG_OFF + (c0 + cw + 4) * 4);
; #pragma unroll
;                         for (int j = 0; j < 4; ++j) { v0[j] = sigmoidf_(v0[j] + g0[j]); v1[j] = sigmoidf_(v1[j] + g1[j]); } }
;                     u32x4 w; w.x = pk2(v0[0], v0[1]); w.y = pk2(v0[2], v0[3]); w.z = pk2(v1[0], v1[1]); w.w = pk2(v1[2], v1[3]);
	v_mul_f32_e32 v151, s66, v151
	v_mul_f32_e32 v152, s66, v152
	v_mul_f32_e32 v153, s66, v153
	v_add_u32_e32 v156, 0xc100, v154
	v_cvt_pk_bf16_f32 v210, v146, v147
	v_cvt_pk_bf16_f32 v211, v148, v149
	v_cvt_pk_bf16_f32 v212, v150, v151
	v_cvt_pk_bf16_f32 v213, v152, v153
	global_store_dwordx4 v156, v[210:213], s[24:25]
	v_mul_f32_e32 v146, v60, v198
	v_mul_f32_e32 v147, v61, v198
	v_mul_f32_e32 v148, v62, v198
	v_mul_f32_e32 v149, v63, v198
	v_mul_f32_e32 v150, v56, v198
	v_mul_f32_e32 v151, v57, v198
	v_mul_f32_e32 v152, v58, v198
	v_mul_f32_e32 v153, v59, v198
	v_mul_f32_e32 v146, s66, v146
	v_mul_f32_e32 v147, s66, v147
	v_mul_f32_e32 v148, s66, v148
	v_mul_f32_e32 v149, s66, v149
	v_mul_f32_e32 v150, s66, v150
	v_mul_f32_e32 v151, s66, v151
	v_mul_f32_e32 v152, s66, v152
	v_mul_f32_e32 v153, s66, v153
	v_add_u32_e32 v156, 0x20000, v154
	v_cvt_pk_bf16_f32 v206, v146, v147
	v_cvt_pk_bf16_f32 v207, v148, v149
	v_cvt_pk_bf16_f32 v208, v150, v151
	v_cvt_pk_bf16_f32 v209, v152, v153
	global_store_dwordx4 v156, v[206:209], s[24:25]
	v_mul_f32_e32 v146, v28, v198
	v_mul_f32_e32 v147, v29, v198
	v_mul_f32_e32 v148, v30, v198
	v_mul_f32_e32 v149, v31, v198
	v_mul_f32_e32 v150, v24, v198
	v_mul_f32_e32 v151, v25, v198
	v_mul_f32_e32 v152, v26, v198
	v_mul_f32_e32 v153, v27, v198
	v_mul_f32_e32 v146, s66, v146
	v_mul_f32_e32 v147, s66, v147
	v_mul_f32_e32 v148, s66, v148
	v_mul_f32_e32 v149, s66, v149
	v_mul_f32_e32 v150, s66, v150
	v_mul_f32_e32 v151, s66, v151
	v_mul_f32_e32 v152, s66, v152
	v_mul_f32_e32 v153, s66, v153
	v_add_u32_e32 v156, 0x20100, v154
	v_cvt_pk_bf16_f32 v210, v146, v147
	v_cvt_pk_bf16_f32 v211, v148, v149
	v_cvt_pk_bf16_f32 v212, v150, v151
	v_cvt_pk_bf16_f32 v213, v152, v153
	global_store_dwordx4 v156, v[210:213], s[24:25]
	v_mul_f32_e32 v146, v52, v199
	v_mul_f32_e32 v147, v53, v199
	v_mul_f32_e32 v148, v54, v199
	v_mul_f32_e32 v149, v55, v199
	v_mul_f32_e32 v150, v48, v199
	v_mul_f32_e32 v151, v49, v199
	v_mul_f32_e32 v152, v50, v199
	v_mul_f32_e32 v153, v51, v199
	v_mul_f32_e32 v146, s66, v146
	v_mul_f32_e32 v147, s66, v147
	v_mul_f32_e32 v148, s66, v148
	v_mul_f32_e32 v149, s66, v149
	v_mul_f32_e32 v150, s66, v150
	v_mul_f32_e32 v151, s66, v151
	v_mul_f32_e32 v152, s66, v152
	v_mul_f32_e32 v153, s66, v153
	v_add_u32_e32 v156, 0x24000, v154
	v_cvt_pk_bf16_f32 v206, v146, v147
	v_cvt_pk_bf16_f32 v207, v148, v149
	v_cvt_pk_bf16_f32 v208, v150, v151
	v_cvt_pk_bf16_f32 v209, v152, v153
	global_store_dwordx4 v156, v[206:209], s[24:25]
	v_mul_f32_e32 v146, v20, v199
	v_mul_f32_e32 v147, v21, v199
	v_mul_f32_e32 v148, v22, v199
	v_mul_f32_e32 v149, v23, v199
	v_mul_f32_e32 v150, v16, v199
	v_mul_f32_e32 v151, v17, v199
	v_mul_f32_e32 v152, v18, v199
	v_mul_f32_e32 v153, v19, v199
	v_mul_f32_e32 v146, s66, v146
	v_mul_f32_e32 v147, s66, v147
	v_mul_f32_e32 v148, s66, v148
	v_mul_f32_e32 v149, s66, v149
	v_mul_f32_e32 v150, s66, v150
	v_mul_f32_e32 v151, s66, v151
	v_mul_f32_e32 v152, s66, v152
	v_mul_f32_e32 v153, s66, v153
	v_add_u32_e32 v156, 0x24100, v154
	v_cvt_pk_bf16_f32 v210, v146, v147
	v_cvt_pk_bf16_f32 v211, v148, v149
	v_cvt_pk_bf16_f32 v212, v150, v151
	v_cvt_pk_bf16_f32 v213, v152, v153
	global_store_dwordx4 v156, v[210:213], s[24:25]
	v_mul_f32_e32 v146, v44, v194
	v_mul_f32_e32 v147, v45, v194
	v_mul_f32_e32 v148, v46, v194
	v_mul_f32_e32 v149, v47, v194
	v_mul_f32_e32 v150, v40, v194
	v_mul_f32_e32 v151, v41, v194
	v_mul_f32_e32 v152, v42, v194
	v_mul_f32_e32 v153, v43, v194
	v_mul_f32_e32 v146, s66, v146
	v_mul_f32_e32 v147, s66, v147
	v_mul_f32_e32 v148, s66, v148
	v_mul_f32_e32 v149, s66, v149
	v_mul_f32_e32 v150, s66, v150
	v_mul_f32_e32 v151, s66, v151
	v_mul_f32_e32 v152, s66, v152
	v_mul_f32_e32 v153, s66, v153
	v_add_u32_e32 v156, 0x28000, v154
	v_cvt_pk_bf16_f32 v206, v146, v147
	v_cvt_pk_bf16_f32 v207, v148, v149
	v_cvt_pk_bf16_f32 v208, v150, v151
	v_cvt_pk_bf16_f32 v209, v152, v153
	global_store_dwordx4 v156, v[206:209], s[24:25]
	v_mul_f32_e32 v146, v12, v194
	v_mul_f32_e32 v147, v13, v194
	v_mul_f32_e32 v148, v14, v194
	v_mul_f32_e32 v149, v15, v194
	v_mul_f32_e32 v150, v8, v194
	v_mul_f32_e32 v151, v9, v194
	v_mul_f32_e32 v152, v10, v194
	v_mul_f32_e32 v153, v11, v194
	v_mul_f32_e32 v146, s66, v146
	v_mul_f32_e32 v147, s66, v147
	v_mul_f32_e32 v148, s66, v148
	v_mul_f32_e32 v149, s66, v149
	v_mul_f32_e32 v150, s66, v150
	v_mul_f32_e32 v151, s66, v151
	v_mul_f32_e32 v152, s66, v152
	v_mul_f32_e32 v153, s66, v153
	v_add_u32_e32 v156, 0x28100, v154
	v_cvt_pk_bf16_f32 v210, v146, v147
	v_cvt_pk_bf16_f32 v211, v148, v149
	v_cvt_pk_bf16_f32 v212, v150, v151
	v_cvt_pk_bf16_f32 v213, v152, v153
	global_store_dwordx4 v156, v[210:213], s[24:25]
	v_mul_f32_e32 v146, v36, v195
	v_mul_f32_e32 v147, v37, v195
	v_mul_f32_e32 v148, v38, v195
	v_mul_f32_e32 v149, v39, v195
	v_mul_f32_e32 v150, v32, v195
	v_mul_f32_e32 v151, v33, v195
	v_mul_f32_e32 v152, v34, v195
	v_mul_f32_e32 v153, v35, v195
	v_mul_f32_e32 v146, s66, v146
	v_mul_f32_e32 v147, s66, v147
	v_mul_f32_e32 v148, s66, v148
	v_mul_f32_e32 v149, s66, v149
	v_mul_f32_e32 v150, s66, v150
	v_mul_f32_e32 v151, s66, v151
	v_mul_f32_e32 v152, s66, v152
	v_mul_f32_e32 v153, s66, v153
	v_add_u32_e32 v156, 0x2c000, v154
	v_cvt_pk_bf16_f32 v206, v146, v147
	v_cvt_pk_bf16_f32 v207, v148, v149
	v_cvt_pk_bf16_f32 v208, v150, v151
	v_cvt_pk_bf16_f32 v209, v152, v153
	global_store_dwordx4 v156, v[206:209], s[24:25]
	v_mul_f32_e32 v146, v4, v195
	v_mul_f32_e32 v147, v5, v195
	v_mul_f32_e32 v148, v6, v195
	v_mul_f32_e32 v149, v7, v195
	v_mul_f32_e32 v150, v0, v195
	v_mul_f32_e32 v151, v1, v195
	v_mul_f32_e32 v152, v2, v195
	v_mul_f32_e32 v153, v3, v195
	v_mul_f32_e32 v146, s66, v146
	v_mul_f32_e32 v147, s66, v147
	v_mul_f32_e32 v148, s66, v148
	v_mul_f32_e32 v149, s66, v149
	v_mul_f32_e32 v150, s66, v150
	v_mul_f32_e32 v151, s66, v151
	v_mul_f32_e32 v152, s66, v152
	v_mul_f32_e32 v153, s66, v153
	v_add_u32_e32 v156, 0x2c100, v154
	v_cvt_pk_bf16_f32 v210, v146, v147
	v_cvt_pk_bf16_f32 v211, v148, v149
	v_cvt_pk_bf16_f32 v212, v150, v151
	v_cvt_pk_bf16_f32 v213, v152, v153
	global_store_dwordx4 v156, v[210:213], s[24:25]
	s_mov_b64 s[22:23], exec
	s_branch .LBB0_639
; #define LAS __attribute__((address_space(3)))
;     DI void operator()(f32x4 (&acc)[2][2][4][2], const Unit& u, int wr, int wc, int fr, int fq, LAS unsigned char* lds) const {
;     ...
;                     f32x4 v0 = acc[ai][bj][m][0] * rs, v1 = acc[ai][bj][m][1] * rs;
;                     if (gcol < 768 && gcol != 640) {
;                         if (rope_wave) {
;                             const float* rp = ROPE + (size_t)posidx * 16;
;                             const f32x4 cs0 = *(const f32x4*)rp, cs1 = *(const f32x4*)(rp + 4), sn0 = *(const f32x4*)(rp + 8), sn1 = *(const f32x4*)(rp + 12);
;                             f32x4 p0, p1;
; #pragma unroll
;                             for (int j = 0; j < 4; ++j) { p0[j] = __shfl_xor(v0[j], 16); p1[j] = __shfl_xor(v1[j], 16); }
;                             if (fq == 0) { v0 = v0 * cs0 - p0 * sn0; v1 = v1 * cs1 - p1 * sn1; }
;                             else if (fq == 1) { v0 = v0 * cs0 + p0 * sn0; v1 = v1 * cs1 + p1 * sn1; }
;                         }
;                     }
;                     bf16_t* dst; int ld, c0; float* of = nullptr; long orow = -1;
;                     if (gcol < 512) { dst = QA; ld = 512; c0 = gcol; v0 = v0 * QSCALE; v1 = v1 * QSCALE; }
;                     else if (gcol < 640) { dst = KA; ld = 128; c0 = gcol - 512; of = out + (prm ? O_KWP : O_KWS); orow = offA; }
;                     else if (gcol < 768) { dst = VA; ld = 128; c0 = gcol - 640; of = out + (prm ? O_VWP : O_VWS); orow = offA; }
;                     else if (gcol < 1280) { dst = QB; ld = 512; c0 = gcol - 768; v0 = v0 * QSCALE; v1 = v1 * QSCALE; }
;                     else if (gcol < 1792) { dst = KB; ld = 512; c0 = gcol - 1280; of = out + (prm ? O_KBP : O_KBS); orow = offB; }
;                     else if (gcol < 2304) { dst = VB; ld = 512; c0 = gcol - 1792; of = out + (prm ? O_VBP : O_VBS); orow = offB; }
;                     else { dst = GATES; ld = 2048; c0 = gcol - 2304;
;                         const f32x4 g0 = *(const LAS f32x4*)(lds + BG_OFF + (c0 + cw) * 4), g1 = *(const LAS f32x4*)(lds + BG_OFF + (c0 + cw + 4) * 4);
; #pragma unroll
;                         for (int j = 0; j < 4; ++j) { v0[j] = sigmoidf_(v0[j] + g0[j]); v1[j] = sigmoidf_(v1[j] + g1[j]); } }
;                     u32x4 w; w.x = pk2(v0[0], v0[1]); w.y = pk2(v0[2], v0[3]); w.z = pk2(v1[0], v1[1]); w.w = pk2(v1[2], v1[3]);
.Lepf_qa:
	s_cmpk_gt_i32 s96, 0x7f
	s_cbranch_scc1 .Lepf_none
	s_mov_b64 s[24:25], s[74:75]
	s_lshl_b32 s22, s97, 9
	s_and_b64 vcc, exec, s[52:53]
	s_cbranch_vccz .Lepf_qb_body
	s_waitcnt lgkmcnt(0)
	v_lshlrev_b32_e32 v154, 10, v192
	v_lshl_add_u32 v154, v166, 1, v154
	v_add_u32_e32 v154, s22, v154
	v_lshlrev_b32_e32 v155, 6, v171
	v_xor_b32_e32 v157, 16, v229
	v_lshlrev_b32_e32 v157, 2, v157
	v_xor_b32_e32 v200, 1, v169
	v_lshlrev_b32_e32 v200, 31, v200
	s_mov_b32 s0, -1
	s_mov_b32 s1, 0
	ds_read_b128 v[130:133], v155 offset:49152
	ds_read_b128 v[134:137], v155 offset:49168
	ds_read_b128 v[138:141], v155 offset:49184
	ds_read_b128 v[142:145], v155 offset:49200
	v_mul_f32_e32 v146, v126, v220
	v_mul_f32_e32 v147, v127, v220
	v_mul_f32_e32 v148, v128, v220
	v_mul_f32_e32 v149, v129, v220
	v_mul_f32_e32 v150, v122, v220
	v_mul_f32_e32 v151, v123, v220
	v_mul_f32_e32 v152, v124, v220
	v_mul_f32_e32 v153, v125, v220
	s_mov_b64 exec, s[0:1]
	ds_bpermute_b32 v236, v157, v146
	ds_bpermute_b32 v237, v157, v147
	ds_bpermute_b32 v238, v157, v148
	ds_bpermute_b32 v239, v157, v149
	ds_bpermute_b32 v240, v157, v150
	ds_bpermute_b32 v241, v157, v151
	ds_bpermute_b32 v242, v157, v152
	ds_bpermute_b32 v243, v157, v153
	s_waitcnt lgkmcnt(0)
	v_mul_f32_e32 v236, v138, v236
	v_mul_f32_e32 v237, v139, v237
	v_mul_f32_e32 v238, v140, v238
	v_mul_f32_e32 v239, v141, v239
	v_mul_f32_e32 v240, v142, v240
	v_mul_f32_e32 v241, v143, v241
	v_mul_f32_e32 v242, v144, v242
	v_mul_f32_e32 v243, v145, v243
	v_xor_b32_e32 v236, v200, v236
	v_xor_b32_e32 v237, v200, v237
	v_xor_b32_e32 v238, v200, v238
	v_xor_b32_e32 v239, v200, v239
	v_xor_b32_e32 v240, v200, v240
	v_xor_b32_e32 v241, v200, v241
	v_xor_b32_e32 v242, v200, v242
	v_xor_b32_e32 v243, v200, v243
	v_fma_f32 v146, v146, v130, v236
	v_fma_f32 v147, v147, v131, v237
	v_fma_f32 v148, v148, v132, v238
	v_fma_f32 v149, v149, v133, v239
	v_fma_f32 v150, v150, v134, v240
	v_fma_f32 v151, v151, v135, v241
	v_fma_f32 v152, v152, v136, v242
	v_fma_f32 v153, v153, v137, v243
	s_mov_b64 exec, -1
	v_mul_f32_e32 v146, s66, v146
	v_mul_f32_e32 v147, s66, v147
	v_mul_f32_e32 v148, s66, v148
	v_mul_f32_e32 v149, s66, v149
	v_mul_f32_e32 v150, s66, v150
	v_mul_f32_e32 v151, s66, v151
	v_mul_f32_e32 v152, s66, v152
	v_mul_f32_e32 v153, s66, v153
	v_add_u32_e32 v156, 0x0, v154
	v_cvt_pk_bf16_f32 v206, v146, v147
	v_cvt_pk_bf16_f32 v207, v148, v149
	v_cvt_pk_bf16_f32 v208, v150, v151
	v_cvt_pk_bf16_f32 v209, v152, v153
	global_store_dwordx4 v156, v[206:209], s[24:25]
	v_mul_f32_e32 v146, v92, v220
	v_mul_f32_e32 v147, v93, v220
	v_mul_f32_e32 v148, v94, v220
	v_mul_f32_e32 v149, v95, v220
	v_mul_f32_e32 v150, v88, v220
	v_mul_f32_e32 v151, v89, v220
	v_mul_f32_e32 v152, v90, v220
	v_mul_f32_e32 v153, v91, v220
	s_mov_b64 exec, s[0:1]
	ds_bpermute_b32 v236, v157, v146
	ds_bpermute_b32 v237, v157, v147
	ds_bpermute_b32 v238, v157, v148
	ds_bpermute_b32 v239, v157, v149
	ds_bpermute_b32 v240, v157, v150
	ds_bpermute_b32 v241, v157, v151
	ds_bpermute_b32 v242, v157, v152
	ds_bpermute_b32 v243, v157, v153
	s_waitcnt lgkmcnt(0)
	v_mul_f32_e32 v236, v138, v236
	v_mul_f32_e32 v237, v139, v237
	v_mul_f32_e32 v238, v140, v238
	v_mul_f32_e32 v239, v141, v239
	v_mul_f32_e32 v240, v142, v240
	v_mul_f32_e32 v241, v143, v241
	v_mul_f32_e32 v242, v144, v242
	v_mul_f32_e32 v243, v145, v243
	v_xor_b32_e32 v236, v200, v236
	v_xor_b32_e32 v237, v200, v237
	v_xor_b32_e32 v238, v200, v238
	v_xor_b32_e32 v239, v200, v239
	v_xor_b32_e32 v240, v200, v240
	v_xor_b32_e32 v241, v200, v241
	v_xor_b32_e32 v242, v200, v242
	v_xor_b32_e32 v243, v200, v243
	v_fma_f32 v146, v146, v130, v236
	v_fma_f32 v147, v147, v131, v237
	v_fma_f32 v148, v148, v132, v238
	v_fma_f32 v149, v149, v133, v239
	v_fma_f32 v150, v150, v134, v240
	v_fma_f32 v151, v151, v135, v241
	v_fma_f32 v152, v152, v136, v242
	v_fma_f32 v153, v153, v137, v243
	s_mov_b64 exec, -1
	v_mul_f32_e32 v146, s66, v146
	v_mul_f32_e32 v147, s66, v147
	v_mul_f32_e32 v148, s66, v148
	v_mul_f32_e32 v149, s66, v149
	v_mul_f32_e32 v150, s66, v150
	v_mul_f32_e32 v151, s66, v151
	v_mul_f32_e32 v152, s66, v152
	v_mul_f32_e32 v153, s66, v153
	v_add_u32_e32 v156, 0x100, v154
	v_cvt_pk_bf16_f32 v210, v146, v147
	v_cvt_pk_bf16_f32 v211, v148, v149
	v_cvt_pk_bf16_f32 v212, v150, v151
	v_cvt_pk_bf16_f32 v213, v152, v153
	global_store_dwordx4 v156, v[210:213], s[24:25]
	ds_read_b128 v[130:133], v155 offset:50176
	ds_read_b128 v[134:137], v155 offset:50192
	ds_read_b128 v[138:141], v155 offset:50208
	ds_read_b128 v[142:145], v155 offset:50224
	v_mul_f32_e32 v146, v118, v221
	v_mul_f32_e32 v147, v119, v221
	v_mul_f32_e32 v148, v120, v221
	v_mul_f32_e32 v149, v121, v221
	v_mul_f32_e32 v150, v114, v221
	v_mul_f32_e32 v151, v115, v221
	v_mul_f32_e32 v152, v116, v221
	v_mul_f32_e32 v153, v117, v221
	s_mov_b64 exec, s[0:1]
	ds_bpermute_b32 v236, v157, v146
	ds_bpermute_b32 v237, v157, v147
	ds_bpermute_b32 v238, v157, v148
	ds_bpermute_b32 v239, v157, v149
	ds_bpermute_b32 v240, v157, v150
	ds_bpermute_b32 v241, v157, v151
	ds_bpermute_b32 v242, v157, v152
	ds_bpermute_b32 v243, v157, v153
	s_waitcnt lgkmcnt(0)
; #define LAS __attribute__((address_space(3)))
;     DI void operator()(f32x4 (&acc)[2][2][4][2], const Unit& u, int wr, int wc, int fr, int fq, LAS unsigned char* lds) const {
;     ...
;                     f32x4 v0 = acc[ai][bj][m][0] * rs, v1 = acc[ai][bj][m][1] * rs;
;                     if (gcol < 768 && gcol != 640) {
;                         if (rope_wave) {
;                             const float* rp = ROPE + (size_t)posidx * 16;
;                             const f32x4 cs0 = *(const f32x4*)rp, cs1 = *(const f32x4*)(rp + 4), sn0 = *(const f32x4*)(rp + 8), sn1 = *(const f32x4*)(rp + 12);
;                             f32x4 p0, p1;
; #pragma unroll
;                             for (int j = 0; j < 4; ++j) { p0[j] = __shfl_xor(v0[j], 16); p1[j] = __shfl_xor(v1[j], 16); }
;                             if (fq == 0) { v0 = v0 * cs0 - p0 * sn0; v1 = v1 * cs1 - p1 * sn1; }
;                             else if (fq == 1) { v0 = v0 * cs0 + p0 * sn0; v1 = v1 * cs1 + p1 * sn1; }
;                         }
;                     }
;                     bf16_t* dst; int ld, c0; float* of = nullptr; long orow = -1;
;                     if (gcol < 512) { dst = QA; ld = 512; c0 = gcol; v0 = v0 * QSCALE; v1 = v1 * QSCALE; }
;                     else if (gcol < 640) { dst = KA; ld = 128; c0 = gcol - 512; of = out + (prm ? O_KWP : O_KWS); orow = offA; }
;                     else if (gcol < 768) { dst = VA; ld = 128; c0 = gcol - 640; of = out + (prm ? O_VWP : O_VWS); orow = offA; }
;                     else if (gcol < 1280) { dst = QB; ld = 512; c0 = gcol - 768; v0 = v0 * QSCALE; v1 = v1 * QSCALE; }
;                     else if (gcol < 1792) { dst = KB; ld = 512; c0 = gcol - 1280; of = out + (prm ? O_KBP : O_KBS); orow = offB; }
;                     else if (gcol < 2304) { dst = VB; ld = 512; c0 = gcol - 1792; of = out + (prm ? O_VBP : O_VBS); orow = offB; }
;                     else { dst = GATES; ld = 2048; c0 = gcol - 2304;
;                         const f32x4 g0 = *(const LAS f32x4*)(lds + BG_OFF + (c0 + cw) * 4), g1 = *(const LAS f32x4*)(lds + BG_OFF + (c0 + cw + 4) * 4);
; #pragma unroll
;                         for (int j = 0; j < 4; ++j) { v0[j] = sigmoidf_(v0[j] + g0[j]); v1[j] = sigmoidf_(v1[j] + g1[j]); } }
;                     u32x4 w; w.x = pk2(v0[0], v0[1]); w.y = pk2(v0[2], v0[3]); w.z = pk2(v1[0], v1[1]); w.w = pk2(v1[2], v1[3]);
	v_mul_f32_e32 v236, v138, v236
	v_mul_f32_e32 v237, v139, v237
	v_mul_f32_e32 v238, v140, v238
	v_mul_f32_e32 v239, v141, v239
	v_mul_f32_e32 v240, v142, v240
	v_mul_f32_e32 v241, v143, v241
	v_mul_f32_e32 v242, v144, v242
	v_mul_f32_e32 v243, v145, v243
	v_xor_b32_e32 v236, v200, v236
	v_xor_b32_e32 v237, v200, v237
	v_xor_b32_e32 v238, v200, v238
	v_xor_b32_e32 v239, v200, v239
	v_xor_b32_e32 v240, v200, v240
	v_xor_b32_e32 v241, v200, v241
	v_xor_b32_e32 v242, v200, v242
	v_xor_b32_e32 v243, v200, v243
	v_fma_f32 v146, v146, v130, v236
	v_fma_f32 v147, v147, v131, v237
	v_fma_f32 v148, v148, v132, v238
	v_fma_f32 v149, v149, v133, v239
	v_fma_f32 v150, v150, v134, v240
	v_fma_f32 v151, v151, v135, v241
	v_fma_f32 v152, v152, v136, v242
	v_fma_f32 v153, v153, v137, v243
	s_mov_b64 exec, -1
	v_mul_f32_e32 v146, s66, v146
	v_mul_f32_e32 v147, s66, v147
	v_mul_f32_e32 v148, s66, v148
	v_mul_f32_e32 v149, s66, v149
	v_mul_f32_e32 v150, s66, v150
	v_mul_f32_e32 v151, s66, v151
	v_mul_f32_e32 v152, s66, v152
	v_mul_f32_e32 v153, s66, v153
	v_add_u32_e32 v156, 0x4000, v154
	v_cvt_pk_bf16_f32 v206, v146, v147
	v_cvt_pk_bf16_f32 v207, v148, v149
	v_cvt_pk_bf16_f32 v208, v150, v151
	v_cvt_pk_bf16_f32 v209, v152, v153
	global_store_dwordx4 v156, v[206:209], s[24:25]
	v_mul_f32_e32 v146, v84, v221
	v_mul_f32_e32 v147, v85, v221
	v_mul_f32_e32 v148, v86, v221
	v_mul_f32_e32 v149, v87, v221
	v_mul_f32_e32 v150, v80, v221
	v_mul_f32_e32 v151, v81, v221
	v_mul_f32_e32 v152, v82, v221
	v_mul_f32_e32 v153, v83, v221
	s_mov_b64 exec, s[0:1]
	ds_bpermute_b32 v236, v157, v146
	ds_bpermute_b32 v237, v157, v147
	ds_bpermute_b32 v238, v157, v148
	ds_bpermute_b32 v239, v157, v149
	ds_bpermute_b32 v240, v157, v150
	ds_bpermute_b32 v241, v157, v151
	ds_bpermute_b32 v242, v157, v152
	ds_bpermute_b32 v243, v157, v153
	s_waitcnt lgkmcnt(0)
	v_mul_f32_e32 v236, v138, v236
	v_mul_f32_e32 v237, v139, v237
	v_mul_f32_e32 v238, v140, v238
	v_mul_f32_e32 v239, v141, v239
	v_mul_f32_e32 v240, v142, v240
	v_mul_f32_e32 v241, v143, v241
	v_mul_f32_e32 v242, v144, v242
	v_mul_f32_e32 v243, v145, v243
	v_xor_b32_e32 v236, v200, v236
	v_xor_b32_e32 v237, v200, v237
	v_xor_b32_e32 v238, v200, v238
	v_xor_b32_e32 v239, v200, v239
	v_xor_b32_e32 v240, v200, v240
	v_xor_b32_e32 v241, v200, v241
	v_xor_b32_e32 v242, v200, v242
	v_xor_b32_e32 v243, v200, v243
	v_fma_f32 v146, v146, v130, v236
	v_fma_f32 v147, v147, v131, v237
	v_fma_f32 v148, v148, v132, v238
	v_fma_f32 v149, v149, v133, v239
	v_fma_f32 v150, v150, v134, v240
	v_fma_f32 v151, v151, v135, v241
	v_fma_f32 v152, v152, v136, v242
	v_fma_f32 v153, v153, v137, v243
	s_mov_b64 exec, -1
	v_mul_f32_e32 v146, s66, v146
	v_mul_f32_e32 v147, s66, v147
	v_mul_f32_e32 v148, s66, v148
	v_mul_f32_e32 v149, s66, v149
	v_mul_f32_e32 v150, s66, v150
	v_mul_f32_e32 v151, s66, v151
	v_mul_f32_e32 v152, s66, v152
	v_mul_f32_e32 v153, s66, v153
	v_add_u32_e32 v156, 0x4100, v154
	v_cvt_pk_bf16_f32 v210, v146, v147
	v_cvt_pk_bf16_f32 v211, v148, v149
	v_cvt_pk_bf16_f32 v212, v150, v151
	v_cvt_pk_bf16_f32 v213, v152, v153
	global_store_dwordx4 v156, v[210:213], s[24:25]
	ds_read_b128 v[130:133], v155 offset:51200
	ds_read_b128 v[134:137], v155 offset:51216
	ds_read_b128 v[138:141], v155 offset:51232
	ds_read_b128 v[142:145], v155 offset:51248
	v_mul_f32_e32 v146, v110, v204
	v_mul_f32_e32 v147, v111, v204
	v_mul_f32_e32 v148, v112, v204
	v_mul_f32_e32 v149, v113, v204
	v_mul_f32_e32 v150, v106, v204
	v_mul_f32_e32 v151, v107, v204
	v_mul_f32_e32 v152, v108, v204
	v_mul_f32_e32 v153, v109, v204
	s_mov_b64 exec, s[0:1]
	ds_bpermute_b32 v236, v157, v146
	ds_bpermute_b32 v237, v157, v147
	ds_bpermute_b32 v238, v157, v148
	ds_bpermute_b32 v239, v157, v149
	ds_bpermute_b32 v240, v157, v150
	ds_bpermute_b32 v241, v157, v151
	ds_bpermute_b32 v242, v157, v152
	ds_bpermute_b32 v243, v157, v153
	s_waitcnt lgkmcnt(0)
	v_mul_f32_e32 v236, v138, v236
	v_mul_f32_e32 v237, v139, v237
	v_mul_f32_e32 v238, v140, v238
	v_mul_f32_e32 v239, v141, v239
	v_mul_f32_e32 v240, v142, v240
	v_mul_f32_e32 v241, v143, v241
	v_mul_f32_e32 v242, v144, v242
	v_mul_f32_e32 v243, v145, v243
	v_xor_b32_e32 v236, v200, v236
	v_xor_b32_e32 v237, v200, v237
	v_xor_b32_e32 v238, v200, v238
	v_xor_b32_e32 v239, v200, v239
	v_xor_b32_e32 v240, v200, v240
	v_xor_b32_e32 v241, v200, v241
	v_xor_b32_e32 v242, v200, v242
	v_xor_b32_e32 v243, v200, v243
	v_fma_f32 v146, v146, v130, v236
	v_fma_f32 v147, v147, v131, v237
	v_fma_f32 v148, v148, v132, v238
	v_fma_f32 v149, v149, v133, v239
	v_fma_f32 v150, v150, v134, v240
	v_fma_f32 v151, v151, v135, v241
	v_fma_f32 v152, v152, v136, v242
	v_fma_f32 v153, v153, v137, v243
	s_mov_b64 exec, -1
	v_mul_f32_e32 v146, s66, v146
	v_mul_f32_e32 v147, s66, v147
	v_mul_f32_e32 v148, s66, v148
	v_mul_f32_e32 v149, s66, v149
	v_mul_f32_e32 v150, s66, v150
	v_mul_f32_e32 v151, s66, v151
	v_mul_f32_e32 v152, s66, v152
	v_mul_f32_e32 v153, s66, v153
	v_add_u32_e32 v156, 0x8000, v154
	v_cvt_pk_bf16_f32 v206, v146, v147
	v_cvt_pk_bf16_f32 v207, v148, v149
	v_cvt_pk_bf16_f32 v208, v150, v151
	v_cvt_pk_bf16_f32 v209, v152, v153
	global_store_dwordx4 v156, v[206:209], s[24:25]
	v_mul_f32_e32 v146, v76, v204
	v_mul_f32_e32 v147, v77, v204
	v_mul_f32_e32 v148, v78, v204
	v_mul_f32_e32 v149, v79, v204
	v_mul_f32_e32 v150, v72, v204
	v_mul_f32_e32 v151, v73, v204
	v_mul_f32_e32 v152, v74, v204
	v_mul_f32_e32 v153, v75, v204
	s_mov_b64 exec, s[0:1]
	ds_bpermute_b32 v236, v157, v146
	ds_bpermute_b32 v237, v157, v147
	ds_bpermute_b32 v238, v157, v148
	ds_bpermute_b32 v239, v157, v149
	ds_bpermute_b32 v240, v157, v150
	ds_bpermute_b32 v241, v157, v151
	ds_bpermute_b32 v242, v157, v152
	ds_bpermute_b32 v243, v157, v153
	s_waitcnt lgkmcnt(0)
; #define LAS __attribute__((address_space(3)))
;     DI void operator()(f32x4 (&acc)[2][2][4][2], const Unit& u, int wr, int wc, int fr, int fq, LAS unsigned char* lds) const {
;     ...
;                     f32x4 v0 = acc[ai][bj][m][0] * rs, v1 = acc[ai][bj][m][1] * rs;
;                     if (gcol < 768 && gcol != 640) {
;                         if (rope_wave) {
;                             const float* rp = ROPE + (size_t)posidx * 16;
;                             const f32x4 cs0 = *(const f32x4*)rp, cs1 = *(const f32x4*)(rp + 4), sn0 = *(const f32x4*)(rp + 8), sn1 = *(const f32x4*)(rp + 12);
;                             f32x4 p0, p1;
; #pragma unroll
;                             for (int j = 0; j < 4; ++j) { p0[j] = __shfl_xor(v0[j], 16); p1[j] = __shfl_xor(v1[j], 16); }
;                             if (fq == 0) { v0 = v0 * cs0 - p0 * sn0; v1 = v1 * cs1 - p1 * sn1; }
;                             else if (fq == 1) { v0 = v0 * cs0 + p0 * sn0; v1 = v1 * cs1 + p1 * sn1; }
;                         }
;                     }
;                     bf16_t* dst; int ld, c0; float* of = nullptr; long orow = -1;
;                     if (gcol < 512) { dst = QA; ld = 512; c0 = gcol; v0 = v0 * QSCALE; v1 = v1 * QSCALE; }
;                     else if (gcol < 640) { dst = KA; ld = 128; c0 = gcol - 512; of = out + (prm ? O_KWP : O_KWS); orow = offA; }
;                     else if (gcol < 768) { dst = VA; ld = 128; c0 = gcol - 640; of = out + (prm ? O_VWP : O_VWS); orow = offA; }
;                     else if (gcol < 1280) { dst = QB; ld = 512; c0 = gcol - 768; v0 = v0 * QSCALE; v1 = v1 * QSCALE; }
;                     else if (gcol < 1792) { dst = KB; ld = 512; c0 = gcol - 1280; of = out + (prm ? O_KBP : O_KBS); orow = offB; }
;                     else if (gcol < 2304) { dst = VB; ld = 512; c0 = gcol - 1792; of = out + (prm ? O_VBP : O_VBS); orow = offB; }
;                     else { dst = GATES; ld = 2048; c0 = gcol - 2304;
;                         const f32x4 g0 = *(const LAS f32x4*)(lds + BG_OFF + (c0 + cw) * 4), g1 = *(const LAS f32x4*)(lds + BG_OFF + (c0 + cw + 4) * 4);
; #pragma unroll
;                         for (int j = 0; j < 4; ++j) { v0[j] = sigmoidf_(v0[j] + g0[j]); v1[j] = sigmoidf_(v1[j] + g1[j]); } }
;                     u32x4 w; w.x = pk2(v0[0], v0[1]); w.y = pk2(v0[2], v0[3]); w.z = pk2(v1[0], v1[1]); w.w = pk2(v1[2], v1[3]);
	v_mul_f32_e32 v236, v138, v236
	v_mul_f32_e32 v237, v139, v237
	v_mul_f32_e32 v238, v140, v238
	v_mul_f32_e32 v239, v141, v239
	v_mul_f32_e32 v240, v142, v240
	v_mul_f32_e32 v241, v143, v241
	v_mul_f32_e32 v242, v144, v242
	v_mul_f32_e32 v243, v145, v243
	v_xor_b32_e32 v236, v200, v236
	v_xor_b32_e32 v237, v200, v237
	v_xor_b32_e32 v238, v200, v238
	v_xor_b32_e32 v239, v200, v239
	v_xor_b32_e32 v240, v200, v240
	v_xor_b32_e32 v241, v200, v241
	v_xor_b32_e32 v242, v200, v242
	v_xor_b32_e32 v243, v200, v243
	v_fma_f32 v146, v146, v130, v236
	v_fma_f32 v147, v147, v131, v237
	v_fma_f32 v148, v148, v132, v238
	v_fma_f32 v149, v149, v133, v239
	v_fma_f32 v150, v150, v134, v240
	v_fma_f32 v151, v151, v135, v241
	v_fma_f32 v152, v152, v136, v242
	v_fma_f32 v153, v153, v137, v243
	s_mov_b64 exec, -1
	v_mul_f32_e32 v146, s66, v146
	v_mul_f32_e32 v147, s66, v147
	v_mul_f32_e32 v148, s66, v148
	v_mul_f32_e32 v149, s66, v149
	v_mul_f32_e32 v150, s66, v150
	v_mul_f32_e32 v151, s66, v151
	v_mul_f32_e32 v152, s66, v152
	v_mul_f32_e32 v153, s66, v153
	v_add_u32_e32 v156, 0x8100, v154
	v_cvt_pk_bf16_f32 v210, v146, v147
	v_cvt_pk_bf16_f32 v211, v148, v149
	v_cvt_pk_bf16_f32 v212, v150, v151
	v_cvt_pk_bf16_f32 v213, v152, v153
	global_store_dwordx4 v156, v[210:213], s[24:25]
	ds_read_b128 v[130:133], v155 offset:52224
	ds_read_b128 v[134:137], v155 offset:52240
	ds_read_b128 v[138:141], v155 offset:52256
	ds_read_b128 v[142:145], v155 offset:52272
	v_mul_f32_e32 v146, v102, v205
	v_mul_f32_e32 v147, v103, v205
	v_mul_f32_e32 v148, v104, v205
	v_mul_f32_e32 v149, v105, v205
	v_mul_f32_e32 v150, v98, v205
	v_mul_f32_e32 v151, v99, v205
	v_mul_f32_e32 v152, v100, v205
	v_mul_f32_e32 v153, v101, v205
	s_mov_b64 exec, s[0:1]
	ds_bpermute_b32 v236, v157, v146
	ds_bpermute_b32 v237, v157, v147
	ds_bpermute_b32 v238, v157, v148
	ds_bpermute_b32 v239, v157, v149
	ds_bpermute_b32 v240, v157, v150
	ds_bpermute_b32 v241, v157, v151
	ds_bpermute_b32 v242, v157, v152
	ds_bpermute_b32 v243, v157, v153
	s_waitcnt lgkmcnt(0)
	v_mul_f32_e32 v236, v138, v236
	v_mul_f32_e32 v237, v139, v237
	v_mul_f32_e32 v238, v140, v238
	v_mul_f32_e32 v239, v141, v239
	v_mul_f32_e32 v240, v142, v240
	v_mul_f32_e32 v241, v143, v241
	v_mul_f32_e32 v242, v144, v242
	v_mul_f32_e32 v243, v145, v243
	v_xor_b32_e32 v236, v200, v236
	v_xor_b32_e32 v237, v200, v237
	v_xor_b32_e32 v238, v200, v238
	v_xor_b32_e32 v239, v200, v239
	v_xor_b32_e32 v240, v200, v240
	v_xor_b32_e32 v241, v200, v241
	v_xor_b32_e32 v242, v200, v242
	v_xor_b32_e32 v243, v200, v243
	v_fma_f32 v146, v146, v130, v236
	v_fma_f32 v147, v147, v131, v237
	v_fma_f32 v148, v148, v132, v238
	v_fma_f32 v149, v149, v133, v239
	v_fma_f32 v150, v150, v134, v240
	v_fma_f32 v151, v151, v135, v241
	v_fma_f32 v152, v152, v136, v242
	v_fma_f32 v153, v153, v137, v243
	s_mov_b64 exec, -1
	v_mul_f32_e32 v146, s66, v146
	v_mul_f32_e32 v147, s66, v147
	v_mul_f32_e32 v148, s66, v148
	v_mul_f32_e32 v149, s66, v149
	v_mul_f32_e32 v150, s66, v150
	v_mul_f32_e32 v151, s66, v151
	v_mul_f32_e32 v152, s66, v152
	v_mul_f32_e32 v153, s66, v153
	v_add_u32_e32 v156, 0xc000, v154
	v_cvt_pk_bf16_f32 v206, v146, v147
	v_cvt_pk_bf16_f32 v207, v148, v149
	v_cvt_pk_bf16_f32 v208, v150, v151
	v_cvt_pk_bf16_f32 v209, v152, v153
	global_store_dwordx4 v156, v[206:209], s[24:25]
	v_mul_f32_e32 v146, v68, v205
	v_mul_f32_e32 v147, v69, v205
	v_mul_f32_e32 v148, v70, v205
	v_mul_f32_e32 v149, v71, v205
	v_mul_f32_e32 v150, v64, v205
	v_mul_f32_e32 v151, v65, v205
	v_mul_f32_e32 v152, v66, v205
	v_mul_f32_e32 v153, v67, v205
	s_mov_b64 exec, s[0:1]
	ds_bpermute_b32 v236, v157, v146
	ds_bpermute_b32 v237, v157, v147
	ds_bpermute_b32 v238, v157, v148
	ds_bpermute_b32 v239, v157, v149
	ds_bpermute_b32 v240, v157, v150
	ds_bpermute_b32 v241, v157, v151
	ds_bpermute_b32 v242, v157, v152
	ds_bpermute_b32 v243, v157, v153
	s_waitcnt lgkmcnt(0)
	v_mul_f32_e32 v236, v138, v236
	v_mul_f32_e32 v237, v139, v237
	v_mul_f32_e32 v238, v140, v238
	v_mul_f32_e32 v239, v141, v239
	v_mul_f32_e32 v240, v142, v240
	v_mul_f32_e32 v241, v143, v241
	v_mul_f32_e32 v242, v144, v242
	v_mul_f32_e32 v243, v145, v243
	v_xor_b32_e32 v236, v200, v236
	v_xor_b32_e32 v237, v200, v237
	v_xor_b32_e32 v238, v200, v238
	v_xor_b32_e32 v239, v200, v239
	v_xor_b32_e32 v240, v200, v240
	v_xor_b32_e32 v241, v200, v241
	v_xor_b32_e32 v242, v200, v242
	v_xor_b32_e32 v243, v200, v243
	v_fma_f32 v146, v146, v130, v236
	v_fma_f32 v147, v147, v131, v237
	v_fma_f32 v148, v148, v132, v238
	v_fma_f32 v149, v149, v133, v239
	v_fma_f32 v150, v150, v134, v240
	v_fma_f32 v151, v151, v135, v241
	v_fma_f32 v152, v152, v136, v242
	v_fma_f32 v153, v153, v137, v243
	s_mov_b64 exec, -1
	v_mul_f32_e32 v146, s66, v146
	v_mul_f32_e32 v147, s66, v147
	v_mul_f32_e32 v148, s66, v148
	v_mul_f32_e32 v149, s66, v149
	v_mul_f32_e32 v150, s66, v150
	v_mul_f32_e32 v151, s66, v151
	v_mul_f32_e32 v152, s66, v152
	v_mul_f32_e32 v153, s66, v153
	v_add_u32_e32 v156, 0xc100, v154
	v_cvt_pk_bf16_f32 v210, v146, v147
	v_cvt_pk_bf16_f32 v211, v148, v149
	v_cvt_pk_bf16_f32 v212, v150, v151
	v_cvt_pk_bf16_f32 v213, v152, v153
	global_store_dwordx4 v156, v[210:213], s[24:25]
	ds_read_b128 v[130:133], v155 offset:57344
	ds_read_b128 v[134:137], v155 offset:57360
	ds_read_b128 v[138:141], v155 offset:57376
	ds_read_b128 v[142:145], v155 offset:57392
	v_mul_f32_e32 v146, v60, v198
	v_mul_f32_e32 v147, v61, v198
	v_mul_f32_e32 v148, v62, v198
	v_mul_f32_e32 v149, v63, v198
	v_mul_f32_e32 v150, v56, v198
	v_mul_f32_e32 v151, v57, v198
	v_mul_f32_e32 v152, v58, v198
	v_mul_f32_e32 v153, v59, v198
	s_mov_b64 exec, s[0:1]
	ds_bpermute_b32 v236, v157, v146
	ds_bpermute_b32 v237, v157, v147
	ds_bpermute_b32 v238, v157, v148
	ds_bpermute_b32 v239, v157, v149
	ds_bpermute_b32 v240, v157, v150
	ds_bpermute_b32 v241, v157, v151
	ds_bpermute_b32 v242, v157, v152
	ds_bpermute_b32 v243, v157, v153
	s_waitcnt lgkmcnt(0)
; #define LAS __attribute__((address_space(3)))
;     DI void operator()(f32x4 (&acc)[2][2][4][2], const Unit& u, int wr, int wc, int fr, int fq, LAS unsigned char* lds) const {
;     ...
;                     f32x4 v0 = acc[ai][bj][m][0] * rs, v1 = acc[ai][bj][m][1] * rs;
;                     if (gcol < 768 && gcol != 640) {
;                         if (rope_wave) {
;                             const float* rp = ROPE + (size_t)posidx * 16;
;                             const f32x4 cs0 = *(const f32x4*)rp, cs1 = *(const f32x4*)(rp + 4), sn0 = *(const f32x4*)(rp + 8), sn1 = *(const f32x4*)(rp + 12);
;                             f32x4 p0, p1;
; #pragma unroll
;                             for (int j = 0; j < 4; ++j) { p0[j] = __shfl_xor(v0[j], 16); p1[j] = __shfl_xor(v1[j], 16); }
;                             if (fq == 0) { v0 = v0 * cs0 - p0 * sn0; v1 = v1 * cs1 - p1 * sn1; }
;                             else if (fq == 1) { v0 = v0 * cs0 + p0 * sn0; v1 = v1 * cs1 + p1 * sn1; }
;                         }
;                     }
;                     bf16_t* dst; int ld, c0; float* of = nullptr; long orow = -1;
;                     if (gcol < 512) { dst = QA; ld = 512; c0 = gcol; v0 = v0 * QSCALE; v1 = v1 * QSCALE; }
;                     else if (gcol < 640) { dst = KA; ld = 128; c0 = gcol - 512; of = out + (prm ? O_KWP : O_KWS); orow = offA; }
;                     else if (gcol < 768) { dst = VA; ld = 128; c0 = gcol - 640; of = out + (prm ? O_VWP : O_VWS); orow = offA; }
;                     else if (gcol < 1280) { dst = QB; ld = 512; c0 = gcol - 768; v0 = v0 * QSCALE; v1 = v1 * QSCALE; }
;                     else if (gcol < 1792) { dst = KB; ld = 512; c0 = gcol - 1280; of = out + (prm ? O_KBP : O_KBS); orow = offB; }
;                     else if (gcol < 2304) { dst = VB; ld = 512; c0 = gcol - 1792; of = out + (prm ? O_VBP : O_VBS); orow = offB; }
;                     else { dst = GATES; ld = 2048; c0 = gcol - 2304;
;                         const f32x4 g0 = *(const LAS f32x4*)(lds + BG_OFF + (c0 + cw) * 4), g1 = *(const LAS f32x4*)(lds + BG_OFF + (c0 + cw + 4) * 4);
; #pragma unroll
;                         for (int j = 0; j < 4; ++j) { v0[j] = sigmoidf_(v0[j] + g0[j]); v1[j] = sigmoidf_(v1[j] + g1[j]); } }
;                     u32x4 w; w.x = pk2(v0[0], v0[1]); w.y = pk2(v0[2], v0[3]); w.z = pk2(v1[0], v1[1]); w.w = pk2(v1[2], v1[3]);
	v_mul_f32_e32 v236, v138, v236
	v_mul_f32_e32 v237, v139, v237
	v_mul_f32_e32 v238, v140, v238
	v_mul_f32_e32 v239, v141, v239
	v_mul_f32_e32 v240, v142, v240
	v_mul_f32_e32 v241, v143, v241
	v_mul_f32_e32 v242, v144, v242
	v_mul_f32_e32 v243, v145, v243
	v_xor_b32_e32 v236, v200, v236
	v_xor_b32_e32 v237, v200, v237
	v_xor_b32_e32 v238, v200, v238
	v_xor_b32_e32 v239, v200, v239
	v_xor_b32_e32 v240, v200, v240
	v_xor_b32_e32 v241, v200, v241
	v_xor_b32_e32 v242, v200, v242
	v_xor_b32_e32 v243, v200, v243
	v_fma_f32 v146, v146, v130, v236
	v_fma_f32 v147, v147, v131, v237
	v_fma_f32 v148, v148, v132, v238
	v_fma_f32 v149, v149, v133, v239
	v_fma_f32 v150, v150, v134, v240
	v_fma_f32 v151, v151, v135, v241
	v_fma_f32 v152, v152, v136, v242
	v_fma_f32 v153, v153, v137, v243
	s_mov_b64 exec, -1
	v_mul_f32_e32 v146, s66, v146
	v_mul_f32_e32 v147, s66, v147
	v_mul_f32_e32 v148, s66, v148
	v_mul_f32_e32 v149, s66, v149
	v_mul_f32_e32 v150, s66, v150
	v_mul_f32_e32 v151, s66, v151
	v_mul_f32_e32 v152, s66, v152
	v_mul_f32_e32 v153, s66, v153
	v_add_u32_e32 v156, 0x20000, v154
	v_cvt_pk_bf16_f32 v206, v146, v147
	v_cvt_pk_bf16_f32 v207, v148, v149
	v_cvt_pk_bf16_f32 v208, v150, v151
	v_cvt_pk_bf16_f32 v209, v152, v153
	global_store_dwordx4 v156, v[206:209], s[24:25]
	v_mul_f32_e32 v146, v28, v198
	v_mul_f32_e32 v147, v29, v198
	v_mul_f32_e32 v148, v30, v198
	v_mul_f32_e32 v149, v31, v198
	v_mul_f32_e32 v150, v24, v198
	v_mul_f32_e32 v151, v25, v198
	v_mul_f32_e32 v152, v26, v198
	v_mul_f32_e32 v153, v27, v198
	s_mov_b64 exec, s[0:1]
	ds_bpermute_b32 v236, v157, v146
	ds_bpermute_b32 v237, v157, v147
	ds_bpermute_b32 v238, v157, v148
	ds_bpermute_b32 v239, v157, v149
	ds_bpermute_b32 v240, v157, v150
	ds_bpermute_b32 v241, v157, v151
	ds_bpermute_b32 v242, v157, v152
	ds_bpermute_b32 v243, v157, v153
	s_waitcnt lgkmcnt(0)
	v_mul_f32_e32 v236, v138, v236
	v_mul_f32_e32 v237, v139, v237
	v_mul_f32_e32 v238, v140, v238
	v_mul_f32_e32 v239, v141, v239
	v_mul_f32_e32 v240, v142, v240
	v_mul_f32_e32 v241, v143, v241
	v_mul_f32_e32 v242, v144, v242
	v_mul_f32_e32 v243, v145, v243
	v_xor_b32_e32 v236, v200, v236
	v_xor_b32_e32 v237, v200, v237
	v_xor_b32_e32 v238, v200, v238
	v_xor_b32_e32 v239, v200, v239
	v_xor_b32_e32 v240, v200, v240
	v_xor_b32_e32 v241, v200, v241
	v_xor_b32_e32 v242, v200, v242
	v_xor_b32_e32 v243, v200, v243
	v_fma_f32 v146, v146, v130, v236
	v_fma_f32 v147, v147, v131, v237
	v_fma_f32 v148, v148, v132, v238
	v_fma_f32 v149, v149, v133, v239
	v_fma_f32 v150, v150, v134, v240
	v_fma_f32 v151, v151, v135, v241
	v_fma_f32 v152, v152, v136, v242
	v_fma_f32 v153, v153, v137, v243
	s_mov_b64 exec, -1
	v_mul_f32_e32 v146, s66, v146
	v_mul_f32_e32 v147, s66, v147
	v_mul_f32_e32 v148, s66, v148
	v_mul_f32_e32 v149, s66, v149
	v_mul_f32_e32 v150, s66, v150
	v_mul_f32_e32 v151, s66, v151
	v_mul_f32_e32 v152, s66, v152
	v_mul_f32_e32 v153, s66, v153
	v_add_u32_e32 v156, 0x20100, v154
	v_cvt_pk_bf16_f32 v210, v146, v147
	v_cvt_pk_bf16_f32 v211, v148, v149
	v_cvt_pk_bf16_f32 v212, v150, v151
	v_cvt_pk_bf16_f32 v213, v152, v153
	global_store_dwordx4 v156, v[210:213], s[24:25]
	ds_read_b128 v[130:133], v155 offset:58368
	ds_read_b128 v[134:137], v155 offset:58384
	ds_read_b128 v[138:141], v155 offset:58400
	ds_read_b128 v[142:145], v155 offset:58416
	v_mul_f32_e32 v146, v52, v199
	v_mul_f32_e32 v147, v53, v199
	v_mul_f32_e32 v148, v54, v199
	v_mul_f32_e32 v149, v55, v199
	v_mul_f32_e32 v150, v48, v199
	v_mul_f32_e32 v151, v49, v199
	v_mul_f32_e32 v152, v50, v199
	v_mul_f32_e32 v153, v51, v199
	s_mov_b64 exec, s[0:1]
	ds_bpermute_b32 v236, v157, v146
	ds_bpermute_b32 v237, v157, v147
	ds_bpermute_b32 v238, v157, v148
	ds_bpermute_b32 v239, v157, v149
	ds_bpermute_b32 v240, v157, v150
	ds_bpermute_b32 v241, v157, v151
	ds_bpermute_b32 v242, v157, v152
	ds_bpermute_b32 v243, v157, v153
	s_waitcnt lgkmcnt(0)
	v_mul_f32_e32 v236, v138, v236
	v_mul_f32_e32 v237, v139, v237
	v_mul_f32_e32 v238, v140, v238
	v_mul_f32_e32 v239, v141, v239
	v_mul_f32_e32 v240, v142, v240
	v_mul_f32_e32 v241, v143, v241
	v_mul_f32_e32 v242, v144, v242
	v_mul_f32_e32 v243, v145, v243
	v_xor_b32_e32 v236, v200, v236
	v_xor_b32_e32 v237, v200, v237
	v_xor_b32_e32 v238, v200, v238
	v_xor_b32_e32 v239, v200, v239
	v_xor_b32_e32 v240, v200, v240
	v_xor_b32_e32 v241, v200, v241
	v_xor_b32_e32 v242, v200, v242
	v_xor_b32_e32 v243, v200, v243
	v_fma_f32 v146, v146, v130, v236
	v_fma_f32 v147, v147, v131, v237
	v_fma_f32 v148, v148, v132, v238
	v_fma_f32 v149, v149, v133, v239
	v_fma_f32 v150, v150, v134, v240
	v_fma_f32 v151, v151, v135, v241
	v_fma_f32 v152, v152, v136, v242
	v_fma_f32 v153, v153, v137, v243
	s_mov_b64 exec, -1
	v_mul_f32_e32 v146, s66, v146
	v_mul_f32_e32 v147, s66, v147
	v_mul_f32_e32 v148, s66, v148
	v_mul_f32_e32 v149, s66, v149
	v_mul_f32_e32 v150, s66, v150
	v_mul_f32_e32 v151, s66, v151
	v_mul_f32_e32 v152, s66, v152
	v_mul_f32_e32 v153, s66, v153
	v_add_u32_e32 v156, 0x24000, v154
	v_cvt_pk_bf16_f32 v206, v146, v147
	v_cvt_pk_bf16_f32 v207, v148, v149
	v_cvt_pk_bf16_f32 v208, v150, v151
	v_cvt_pk_bf16_f32 v209, v152, v153
	global_store_dwordx4 v156, v[206:209], s[24:25]
	v_mul_f32_e32 v146, v20, v199
	v_mul_f32_e32 v147, v21, v199
	v_mul_f32_e32 v148, v22, v199
	v_mul_f32_e32 v149, v23, v199
	v_mul_f32_e32 v150, v16, v199
	v_mul_f32_e32 v151, v17, v199
	v_mul_f32_e32 v152, v18, v199
	v_mul_f32_e32 v153, v19, v199
	s_mov_b64 exec, s[0:1]
	ds_bpermute_b32 v236, v157, v146
	ds_bpermute_b32 v237, v157, v147
	ds_bpermute_b32 v238, v157, v148
	ds_bpermute_b32 v239, v157, v149
	ds_bpermute_b32 v240, v157, v150
	ds_bpermute_b32 v241, v157, v151
	ds_bpermute_b32 v242, v157, v152
	ds_bpermute_b32 v243, v157, v153
	s_waitcnt lgkmcnt(0)
; #define LAS __attribute__((address_space(3)))
;     DI void operator()(f32x4 (&acc)[2][2][4][2], const Unit& u, int wr, int wc, int fr, int fq, LAS unsigned char* lds) const {
;     ...
;                     f32x4 v0 = acc[ai][bj][m][0] * rs, v1 = acc[ai][bj][m][1] * rs;
;                     if (gcol < 768 && gcol != 640) {
;                         if (rope_wave) {
;                             const float* rp = ROPE + (size_t)posidx * 16;
;                             const f32x4 cs0 = *(const f32x4*)rp, cs1 = *(const f32x4*)(rp + 4), sn0 = *(const f32x4*)(rp + 8), sn1 = *(const f32x4*)(rp + 12);
;                             f32x4 p0, p1;
; #pragma unroll
;                             for (int j = 0; j < 4; ++j) { p0[j] = __shfl_xor(v0[j], 16); p1[j] = __shfl_xor(v1[j], 16); }
;                             if (fq == 0) { v0 = v0 * cs0 - p0 * sn0; v1 = v1 * cs1 - p1 * sn1; }
;                             else if (fq == 1) { v0 = v0 * cs0 + p0 * sn0; v1 = v1 * cs1 + p1 * sn1; }
;                         }
;                     }
;                     bf16_t* dst; int ld, c0; float* of = nullptr; long orow = -1;
;                     if (gcol < 512) { dst = QA; ld = 512; c0 = gcol; v0 = v0 * QSCALE; v1 = v1 * QSCALE; }
;                     else if (gcol < 640) { dst = KA; ld = 128; c0 = gcol - 512; of = out + (prm ? O_KWP : O_KWS); orow = offA; }
;                     else if (gcol < 768) { dst = VA; ld = 128; c0 = gcol - 640; of = out + (prm ? O_VWP : O_VWS); orow = offA; }
;                     else if (gcol < 1280) { dst = QB; ld = 512; c0 = gcol - 768; v0 = v0 * QSCALE; v1 = v1 * QSCALE; }
;                     else if (gcol < 1792) { dst = KB; ld = 512; c0 = gcol - 1280; of = out + (prm ? O_KBP : O_KBS); orow = offB; }
;                     else if (gcol < 2304) { dst = VB; ld = 512; c0 = gcol - 1792; of = out + (prm ? O_VBP : O_VBS); orow = offB; }
;                     else { dst = GATES; ld = 2048; c0 = gcol - 2304;
;                         const f32x4 g0 = *(const LAS f32x4*)(lds + BG_OFF + (c0 + cw) * 4), g1 = *(const LAS f32x4*)(lds + BG_OFF + (c0 + cw + 4) * 4);
; #pragma unroll
;                         for (int j = 0; j < 4; ++j) { v0[j] = sigmoidf_(v0[j] + g0[j]); v1[j] = sigmoidf_(v1[j] + g1[j]); } }
;                     u32x4 w; w.x = pk2(v0[0], v0[1]); w.y = pk2(v0[2], v0[3]); w.z = pk2(v1[0], v1[1]); w.w = pk2(v1[2], v1[3]);
	v_mul_f32_e32 v236, v138, v236
	v_mul_f32_e32 v237, v139, v237
	v_mul_f32_e32 v238, v140, v238
	v_mul_f32_e32 v239, v141, v239
	v_mul_f32_e32 v240, v142, v240
	v_mul_f32_e32 v241, v143, v241
	v_mul_f32_e32 v242, v144, v242
	v_mul_f32_e32 v243, v145, v243
	v_xor_b32_e32 v236, v200, v236
	v_xor_b32_e32 v237, v200, v237
	v_xor_b32_e32 v238, v200, v238
	v_xor_b32_e32 v239, v200, v239
	v_xor_b32_e32 v240, v200, v240
	v_xor_b32_e32 v241, v200, v241
	v_xor_b32_e32 v242, v200, v242
	v_xor_b32_e32 v243, v200, v243
	v_fma_f32 v146, v146, v130, v236
	v_fma_f32 v147, v147, v131, v237
	v_fma_f32 v148, v148, v132, v238
	v_fma_f32 v149, v149, v133, v239
	v_fma_f32 v150, v150, v134, v240
	v_fma_f32 v151, v151, v135, v241
	v_fma_f32 v152, v152, v136, v242
	v_fma_f32 v153, v153, v137, v243
	s_mov_b64 exec, -1
	v_mul_f32_e32 v146, s66, v146
	v_mul_f32_e32 v147, s66, v147
	v_mul_f32_e32 v148, s66, v148
	v_mul_f32_e32 v149, s66, v149
	v_mul_f32_e32 v150, s66, v150
	v_mul_f32_e32 v151, s66, v151
	v_mul_f32_e32 v152, s66, v152
	v_mul_f32_e32 v153, s66, v153
	v_add_u32_e32 v156, 0x24100, v154
	v_cvt_pk_bf16_f32 v210, v146, v147
	v_cvt_pk_bf16_f32 v211, v148, v149
	v_cvt_pk_bf16_f32 v212, v150, v151
	v_cvt_pk_bf16_f32 v213, v152, v153
	global_store_dwordx4 v156, v[210:213], s[24:25]
	ds_read_b128 v[130:133], v155 offset:59392
	ds_read_b128 v[134:137], v155 offset:59408
	ds_read_b128 v[138:141], v155 offset:59424
	ds_read_b128 v[142:145], v155 offset:59440
	v_mul_f32_e32 v146, v44, v194
	v_mul_f32_e32 v147, v45, v194
	v_mul_f32_e32 v148, v46, v194
	v_mul_f32_e32 v149, v47, v194
	v_mul_f32_e32 v150, v40, v194
	v_mul_f32_e32 v151, v41, v194
	v_mul_f32_e32 v152, v42, v194
	v_mul_f32_e32 v153, v43, v194
	s_mov_b64 exec, s[0:1]
	ds_bpermute_b32 v236, v157, v146
	ds_bpermute_b32 v237, v157, v147
	ds_bpermute_b32 v238, v157, v148
	ds_bpermute_b32 v239, v157, v149
	ds_bpermute_b32 v240, v157, v150
	ds_bpermute_b32 v241, v157, v151
	ds_bpermute_b32 v242, v157, v152
	ds_bpermute_b32 v243, v157, v153
	s_waitcnt lgkmcnt(0)
	v_mul_f32_e32 v236, v138, v236
	v_mul_f32_e32 v237, v139, v237
	v_mul_f32_e32 v238, v140, v238
	v_mul_f32_e32 v239, v141, v239
	v_mul_f32_e32 v240, v142, v240
	v_mul_f32_e32 v241, v143, v241
	v_mul_f32_e32 v242, v144, v242
	v_mul_f32_e32 v243, v145, v243
	v_xor_b32_e32 v236, v200, v236
	v_xor_b32_e32 v237, v200, v237
	v_xor_b32_e32 v238, v200, v238
	v_xor_b32_e32 v239, v200, v239
	v_xor_b32_e32 v240, v200, v240
	v_xor_b32_e32 v241, v200, v241
	v_xor_b32_e32 v242, v200, v242
	v_xor_b32_e32 v243, v200, v243
	v_fma_f32 v146, v146, v130, v236
	v_fma_f32 v147, v147, v131, v237
	v_fma_f32 v148, v148, v132, v238
	v_fma_f32 v149, v149, v133, v239
	v_fma_f32 v150, v150, v134, v240
	v_fma_f32 v151, v151, v135, v241
	v_fma_f32 v152, v152, v136, v242
	v_fma_f32 v153, v153, v137, v243
	s_mov_b64 exec, -1
	v_mul_f32_e32 v146, s66, v146
	v_mul_f32_e32 v147, s66, v147
	v_mul_f32_e32 v148, s66, v148
	v_mul_f32_e32 v149, s66, v149
	v_mul_f32_e32 v150, s66, v150
	v_mul_f32_e32 v151, s66, v151
	v_mul_f32_e32 v152, s66, v152
	v_mul_f32_e32 v153, s66, v153
	v_add_u32_e32 v156, 0x28000, v154
	v_cvt_pk_bf16_f32 v206, v146, v147
	v_cvt_pk_bf16_f32 v207, v148, v149
	v_cvt_pk_bf16_f32 v208, v150, v151
	v_cvt_pk_bf16_f32 v209, v152, v153
	global_store_dwordx4 v156, v[206:209], s[24:25]
	v_mul_f32_e32 v146, v12, v194
	v_mul_f32_e32 v147, v13, v194
	v_mul_f32_e32 v148, v14, v194
	v_mul_f32_e32 v149, v15, v194
	v_mul_f32_e32 v150, v8, v194
	v_mul_f32_e32 v151, v9, v194
	v_mul_f32_e32 v152, v10, v194
	v_mul_f32_e32 v153, v11, v194
	s_mov_b64 exec, s[0:1]
	ds_bpermute_b32 v236, v157, v146
	ds_bpermute_b32 v237, v157, v147
	ds_bpermute_b32 v238, v157, v148
	ds_bpermute_b32 v239, v157, v149
	ds_bpermute_b32 v240, v157, v150
	ds_bpermute_b32 v241, v157, v151
	ds_bpermute_b32 v242, v157, v152
	ds_bpermute_b32 v243, v157, v153
	s_waitcnt lgkmcnt(0)
; #define LAS __attribute__((address_space(3)))
;     DI void operator()(f32x4 (&acc)[2][2][4][2], const Unit& u, int wr, int wc, int fr, int fq, LAS unsigned char* lds) const {
;     ...
;                     f32x4 v0 = acc[ai][bj][m][0] * rs, v1 = acc[ai][bj][m][1] * rs;
;                     if (gcol < 768 && gcol != 640) {
;                         if (rope_wave) {
;                             const float* rp = ROPE + (size_t)posidx * 16;
;                             const f32x4 cs0 = *(const f32x4*)rp, cs1 = *(const f32x4*)(rp + 4), sn0 = *(const f32x4*)(rp + 8), sn1 = *(const f32x4*)(rp + 12);
;                             f32x4 p0, p1;
; #pragma unroll
;                             for (int j = 0; j < 4; ++j) { p0[j] = __shfl_xor(v0[j], 16); p1[j] = __shfl_xor(v1[j], 16); }
;                             if (fq == 0) { v0 = v0 * cs0 - p0 * sn0; v1 = v1 * cs1 - p1 * sn1; }
;                             else if (fq == 1) { v0 = v0 * cs0 + p0 * sn0; v1 = v1 * cs1 + p1 * sn1; }
;                         }
;                     }
;                     bf16_t* dst; int ld, c0; float* of = nullptr; long orow = -1;
;                     if (gcol < 512) { dst = QA; ld = 512; c0 = gcol; v0 = v0 * QSCALE; v1 = v1 * QSCALE; }
;                     else if (gcol < 640) { dst = KA; ld = 128; c0 = gcol - 512; of = out + (prm ? O_KWP : O_KWS); orow = offA; }
;                     else if (gcol < 768) { dst = VA; ld = 128; c0 = gcol - 640; of = out + (prm ? O_VWP : O_VWS); orow = offA; }
;                     else if (gcol < 1280) { dst = QB; ld = 512; c0 = gcol - 768; v0 = v0 * QSCALE; v1 = v1 * QSCALE; }
;                     else if (gcol < 1792) { dst = KB; ld = 512; c0 = gcol - 1280; of = out + (prm ? O_KBP : O_KBS); orow = offB; }
;                     else if (gcol < 2304) { dst = VB; ld = 512; c0 = gcol - 1792; of = out + (prm ? O_VBP : O_VBS); orow = offB; }
;                     else { dst = GATES; ld = 2048; c0 = gcol - 2304;
;                         const f32x4 g0 = *(const LAS f32x4*)(lds + BG_OFF + (c0 + cw) * 4), g1 = *(const LAS f32x4*)(lds + BG_OFF + (c0 + cw + 4) * 4);
; #pragma unroll
;                         for (int j = 0; j < 4; ++j) { v0[j] = sigmoidf_(v0[j] + g0[j]); v1[j] = sigmoidf_(v1[j] + g1[j]); } }
;                     u32x4 w; w.x = pk2(v0[0], v0[1]); w.y = pk2(v0[2], v0[3]); w.z = pk2(v1[0], v1[1]); w.w = pk2(v1[2], v1[3]);
	v_mul_f32_e32 v236, v138, v236
	v_mul_f32_e32 v237, v139, v237
	v_mul_f32_e32 v238, v140, v238
	v_mul_f32_e32 v239, v141, v239
	v_mul_f32_e32 v240, v142, v240
	v_mul_f32_e32 v241, v143, v241
	v_mul_f32_e32 v242, v144, v242
	v_mul_f32_e32 v243, v145, v243
	v_xor_b32_e32 v236, v200, v236
	v_xor_b32_e32 v237, v200, v237
	v_xor_b32_e32 v238, v200, v238
	v_xor_b32_e32 v239, v200, v239
	v_xor_b32_e32 v240, v200, v240
	v_xor_b32_e32 v241, v200, v241
	v_xor_b32_e32 v242, v200, v242
	v_xor_b32_e32 v243, v200, v243
	v_fma_f32 v146, v146, v130, v236
	v_fma_f32 v147, v147, v131, v237
	v_fma_f32 v148, v148, v132, v238
	v_fma_f32 v149, v149, v133, v239
	v_fma_f32 v150, v150, v134, v240
	v_fma_f32 v151, v151, v135, v241
	v_fma_f32 v152, v152, v136, v242
	v_fma_f32 v153, v153, v137, v243
	s_mov_b64 exec, -1
	v_mul_f32_e32 v146, s66, v146
	v_mul_f32_e32 v147, s66, v147
	v_mul_f32_e32 v148, s66, v148
	v_mul_f32_e32 v149, s66, v149
	v_mul_f32_e32 v150, s66, v150
	v_mul_f32_e32 v151, s66, v151
	v_mul_f32_e32 v152, s66, v152
	v_mul_f32_e32 v153, s66, v153
	v_add_u32_e32 v156, 0x28100, v154
	v_cvt_pk_bf16_f32 v210, v146, v147
	v_cvt_pk_bf16_f32 v211, v148, v149
	v_cvt_pk_bf16_f32 v212, v150, v151
	v_cvt_pk_bf16_f32 v213, v152, v153
	global_store_dwordx4 v156, v[210:213], s[24:25]
	ds_read_b128 v[130:133], v155 offset:60416
	ds_read_b128 v[134:137], v155 offset:60432
	ds_read_b128 v[138:141], v155 offset:60448
	ds_read_b128 v[142:145], v155 offset:60464
	v_mul_f32_e32 v146, v36, v195
	v_mul_f32_e32 v147, v37, v195
	v_mul_f32_e32 v148, v38, v195
	v_mul_f32_e32 v149, v39, v195
	v_mul_f32_e32 v150, v32, v195
	v_mul_f32_e32 v151, v33, v195
	v_mul_f32_e32 v152, v34, v195
	v_mul_f32_e32 v153, v35, v195
	s_mov_b64 exec, s[0:1]
	ds_bpermute_b32 v236, v157, v146
	ds_bpermute_b32 v237, v157, v147
	ds_bpermute_b32 v238, v157, v148
	ds_bpermute_b32 v239, v157, v149
	ds_bpermute_b32 v240, v157, v150
	ds_bpermute_b32 v241, v157, v151
	ds_bpermute_b32 v242, v157, v152
	ds_bpermute_b32 v243, v157, v153
	s_waitcnt lgkmcnt(0)
	v_mul_f32_e32 v236, v138, v236
	v_mul_f32_e32 v237, v139, v237
	v_mul_f32_e32 v238, v140, v238
	v_mul_f32_e32 v239, v141, v239
	v_mul_f32_e32 v240, v142, v240
	v_mul_f32_e32 v241, v143, v241
	v_mul_f32_e32 v242, v144, v242
	v_mul_f32_e32 v243, v145, v243
	v_xor_b32_e32 v236, v200, v236
	v_xor_b32_e32 v237, v200, v237
	v_xor_b32_e32 v238, v200, v238
	v_xor_b32_e32 v239, v200, v239
	v_xor_b32_e32 v240, v200, v240
	v_xor_b32_e32 v241, v200, v241
	v_xor_b32_e32 v242, v200, v242
	v_xor_b32_e32 v243, v200, v243
	v_fma_f32 v146, v146, v130, v236
	v_fma_f32 v147, v147, v131, v237
	v_fma_f32 v148, v148, v132, v238
	v_fma_f32 v149, v149, v133, v239
	v_fma_f32 v150, v150, v134, v240
	v_fma_f32 v151, v151, v135, v241
	v_fma_f32 v152, v152, v136, v242
	v_fma_f32 v153, v153, v137, v243
	s_mov_b64 exec, -1
	v_mul_f32_e32 v146, s66, v146
	v_mul_f32_e32 v147, s66, v147
	v_mul_f32_e32 v148, s66, v148
	v_mul_f32_e32 v149, s66, v149
	v_mul_f32_e32 v150, s66, v150
	v_mul_f32_e32 v151, s66, v151
	v_mul_f32_e32 v152, s66, v152
	v_mul_f32_e32 v153, s66, v153
	v_add_u32_e32 v156, 0x2c000, v154
	v_cvt_pk_bf16_f32 v206, v146, v147
	v_cvt_pk_bf16_f32 v207, v148, v149
	v_cvt_pk_bf16_f32 v208, v150, v151
	v_cvt_pk_bf16_f32 v209, v152, v153
	global_store_dwordx4 v156, v[206:209], s[24:25]
	v_mul_f32_e32 v146, v4, v195
	v_mul_f32_e32 v147, v5, v195
	v_mul_f32_e32 v148, v6, v195
	v_mul_f32_e32 v149, v7, v195
	v_mul_f32_e32 v150, v0, v195
	v_mul_f32_e32 v151, v1, v195
	v_mul_f32_e32 v152, v2, v195
	v_mul_f32_e32 v153, v3, v195
	s_mov_b64 exec, s[0:1]
	ds_bpermute_b32 v236, v157, v146
	ds_bpermute_b32 v237, v157, v147
	ds_bpermute_b32 v238, v157, v148
	ds_bpermute_b32 v239, v157, v149
	ds_bpermute_b32 v240, v157, v150
	ds_bpermute_b32 v241, v157, v151
	ds_bpermute_b32 v242, v157, v152
	ds_bpermute_b32 v243, v157, v153
	s_waitcnt lgkmcnt(0)
	v_mul_f32_e32 v236, v138, v236
	v_mul_f32_e32 v237, v139, v237
	v_mul_f32_e32 v238, v140, v238
	v_mul_f32_e32 v239, v141, v239
	v_mul_f32_e32 v240, v142, v240
	v_mul_f32_e32 v241, v143, v241
	v_mul_f32_e32 v242, v144, v242
	v_mul_f32_e32 v243, v145, v243
	v_xor_b32_e32 v236, v200, v236
	v_xor_b32_e32 v237, v200, v237
	v_xor_b32_e32 v238, v200, v238
	v_xor_b32_e32 v239, v200, v239
	v_xor_b32_e32 v240, v200, v240
	v_xor_b32_e32 v241, v200, v241
	v_xor_b32_e32 v242, v200, v242
	v_xor_b32_e32 v243, v200, v243
	v_fma_f32 v146, v146, v130, v236
	v_fma_f32 v147, v147, v131, v237
	v_fma_f32 v148, v148, v132, v238
	v_fma_f32 v149, v149, v133, v239
	v_fma_f32 v150, v150, v134, v240
	v_fma_f32 v151, v151, v135, v241
	v_fma_f32 v152, v152, v136, v242
	v_fma_f32 v153, v153, v137, v243
	s_mov_b64 exec, -1
	v_mul_f32_e32 v146, s66, v146
	v_mul_f32_e32 v147, s66, v147
	v_mul_f32_e32 v148, s66, v148
	v_mul_f32_e32 v149, s66, v149
	v_mul_f32_e32 v150, s66, v150
	v_mul_f32_e32 v151, s66, v151
	v_mul_f32_e32 v152, s66, v152
	v_mul_f32_e32 v153, s66, v153
	v_add_u32_e32 v156, 0x2c100, v154
	v_cvt_pk_bf16_f32 v210, v146, v147
	v_cvt_pk_bf16_f32 v211, v148, v149
	v_cvt_pk_bf16_f32 v212, v150, v151
	v_cvt_pk_bf16_f32 v213, v152, v153
	global_store_dwordx4 v156, v[210:213], s[24:25]
	s_mov_b64 s[22:23], exec
	s_branch .LBB0_639
